# loop-edge: fast paths end with inlined loop control (one taken branch per tile instead of three)
# speedup vs baseline: 1.0019x; 1.0019x over previous
;     ...
;         if (active) {
; #pragma unroll
;             for (int kb = 0; kb < 2; ++kb) {
;                 constexpr int NB = KS / 4;
;                 const bf16_t* kp = Ks + (32 * kb + r) * KLD + 8 * h2;
;                 bf16x8 kf[2][4];
; #pragma unroll
;                 for (int e = 0; e < 4; ++e) kf[0][e] = *(const bf16x8*)(kp + 16 * e);
;                 f32x16 acc; for (int i = 0; i < 16; ++i) acc[i] = 0.f;
; #pragma unroll
;                 for (int bb = 0; bb < NB; ++bb) {
;                     if (bb + 1 < NB) {
; #pragma unroll
;                         for (int e = 0; e < 4; ++e) kf[(bb + 1) & 1][e] = *(const bf16x8*)(kp + 16 * (4 * (bb + 1) + e)); }
;                     __builtin_amdgcn_sched_barrier(0);
; #pragma unroll
;                     for (int e = 0; e < 4; ++e) acc = MFMA32(kf[bb & 1][e], qf[4 * bb + e], acc);
;                     __builtin_amdgcn_sched_barrier(0);
;                 }
;                 sacc[kb] = acc;
;             }
;         }
;         if (j + 1 < ntiles && amode != 5) ATT_ISSUE_K(j + 1);
;         if (active) {
;             const bool masked = (k0 + 63 > q0); const int qpos = q0 + r;
; #pragma unroll
;             for (int kb = 0; kb < 2; ++kb) {
;                 bf16x8 vfa[2][2], vfb[2][2];
; #pragma unroll
;                 for (int d = 0; d < 2; ++d) { vfa[d][0] = ld_perm(Vs + (32 * d + r) * VLD + 32 * kb + 4 * h2); vfa[d][1] = ld_perm(Vs + (32 * d + r) * VLD + 32 * kb + 16 + 4 * h2); }
;                 f32x4 c4[2];
;                 if (DECAY) {
; #pragma unroll
;                     for (int g = 0; g < 2; ++g) c4[g] = *(const f32x4*)(cks + 32 * kb + 8 * g + 4 * h2); }
;                 __builtin_amdgcn_sched_barrier(0);
;                 if (DECAY) {
; #pragma unroll
;                     for (int g = 0; g < 2; ++g)
; #pragma unroll
;                         for (int e = 0; e < 4; ++e) sacc[kb][4 * g + e] -= c4[g][e];
; #pragma unroll
;                     for (int g = 0; g < 2; ++g) c4[g] = *(const f32x4*)(cks + 32 * kb + 8 * (g + 2) + 4 * h2);
; #pragma unroll
;                     for (int g = 0; g < 2; ++g)
; #pragma unroll
;                         for (int e = 0; e < 4; ++e) sacc[kb][4 * (g + 2) + e] -= c4[g][e];
;                 }
;                 if (masked) {
; #pragma unroll
;                     for (int i = 0; i < 16; ++i) { if (k0 + 32 * kb + crow(i, h2) > qpos) sacc[kb][i] = -INFINITY; } }
.Lfox_fast:
	v_add3_u32 v0, s41, v198, v202
	ds_read_b128 v[2:5], v0
	ds_read_b128 v[6:9], v0 offset:32
	ds_read_b128 v[10:13], v0 offset:64
	ds_read_b128 v[148:151], v0 offset:96
	ds_read_b128 v[152:155], v0 offset:128
	ds_read_b128 v[156:159], v0 offset:160
	ds_read_b128 v[172:175], v0 offset:192
	ds_read_b128 v[144:147], v0 offset:224
	s_waitcnt lgkmcnt(7)
	v_mfma_f32_32x32x16_bf16 v[80:95], v[2:5], v[140:143], v[80:95]
	v_mov_b32_e32 v96, v182
	v_mov_b32_e32 v97, v182
	s_waitcnt lgkmcnt(6)
	v_mfma_f32_32x32x16_bf16 v[80:95], v[6:9], v[136:139], v[80:95]
	v_mov_b32_e32 v98, v182
	v_mov_b32_e32 v99, v182
	s_waitcnt lgkmcnt(5)
	v_mfma_f32_32x32x16_bf16 v[80:95], v[10:13], v[132:135], v[80:95]
	v_mov_b32_e32 v100, v182
	v_mov_b32_e32 v101, v182
	s_waitcnt lgkmcnt(4)
	v_mfma_f32_32x32x16_bf16 v[80:95], v[148:151], v[128:131], v[80:95]
	v_mov_b32_e32 v102, v182
	v_mov_b32_e32 v103, v182
	s_waitcnt lgkmcnt(3)
	v_mfma_f32_32x32x16_bf16 v[80:95], v[152:155], v[124:127], v[80:95]
	v_mov_b32_e32 v104, v182
	v_mov_b32_e32 v105, v182
	s_waitcnt lgkmcnt(2)
	v_mfma_f32_32x32x16_bf16 v[80:95], v[156:159], v[120:123], v[80:95]
	v_mov_b32_e32 v106, v182
	v_mov_b32_e32 v107, v182
	s_waitcnt lgkmcnt(1)
	v_mfma_f32_32x32x16_bf16 v[80:95], v[172:175], v[116:119], v[80:95]
	v_mov_b32_e32 v108, v182
	v_mov_b32_e32 v109, v182
	s_waitcnt lgkmcnt(0)
	v_mfma_f32_32x32x16_bf16 v[80:95], v[144:147], v[112:115], v[80:95]
	v_mov_b32_e32 v110, v182
	v_mov_b32_e32 v111, v182
	ds_read_b128 v[2:5], v0 offset:8704
	ds_read_b128 v[6:9], v0 offset:8736
	ds_read_b128 v[10:13], v0 offset:8768
	ds_read_b128 v[144:147], v0 offset:8800
	ds_read_b128 v[148:151], v0 offset:8832
	ds_read_b128 v[152:155], v0 offset:8864
	ds_read_b128 v[156:159], v0 offset:8896
	ds_read_b128 v[172:175], v0 offset:8928
	v_add_u32_e32 v232, s41, v198
	ds_read_b128 v[176:179], v232 offset:34816
	ds_read_b128 v[186:189], v232 offset:34848
	ds_read_b128 v[236:239], v232 offset:34880
	ds_read_b128 v[232:235], v232 offset:34912
	s_waitcnt lgkmcnt(11)
	v_mfma_f32_32x32x16_bf16 v[96:111], v[2:5], v[140:143], v[96:111]
	s_waitcnt lgkmcnt(10)
	v_mfma_f32_32x32x16_bf16 v[96:111], v[6:9], v[136:139], v[96:111]
	s_waitcnt lgkmcnt(0)
	v_sub_f32_e32 v192, v80, v176
	v_exp_f32_e32 v80, v192
	v_mfma_f32_32x32x16_bf16 v[96:111], v[10:13], v[132:135], v[96:111]
	v_sub_f32_e32 v193, v81, v177
	v_exp_f32_e32 v81, v193
	v_sub_f32_e32 v192, v82, v178
	v_exp_f32_e32 v82, v192
	v_sub_f32_e32 v193, v83, v179
	v_exp_f32_e32 v83, v193
	v_mfma_f32_32x32x16_bf16 v[96:111], v[144:147], v[128:131], v[96:111]
	v_sub_f32_e32 v192, v84, v186
	v_exp_f32_e32 v84, v192
	v_sub_f32_e32 v193, v85, v187
	v_exp_f32_e32 v85, v193
	v_sub_f32_e32 v192, v86, v188
	v_exp_f32_e32 v86, v192
	v_mfma_f32_32x32x16_bf16 v[96:111], v[148:151], v[124:127], v[96:111]
	v_sub_f32_e32 v193, v87, v189
	v_exp_f32_e32 v87, v193
	v_sub_f32_e32 v192, v88, v236
	v_exp_f32_e32 v88, v192
	v_sub_f32_e32 v193, v89, v237
	v_exp_f32_e32 v89, v193
	v_mfma_f32_32x32x16_bf16 v[96:111], v[152:155], v[120:123], v[96:111]
	v_sub_f32_e32 v192, v90, v238
	v_exp_f32_e32 v90, v192
	v_sub_f32_e32 v193, v91, v239
	v_exp_f32_e32 v91, v193
	v_sub_f32_e32 v192, v92, v232
	v_exp_f32_e32 v92, v192
	v_mfma_f32_32x32x16_bf16 v[96:111], v[156:159], v[116:119], v[96:111]
	v_sub_f32_e32 v193, v93, v233
	v_exp_f32_e32 v93, v193
	v_sub_f32_e32 v192, v94, v234
	v_exp_f32_e32 v94, v192
	v_sub_f32_e32 v193, v95, v235
	v_exp_f32_e32 v95, v193
	v_mfma_f32_32x32x16_bf16 v[96:111], v[172:175], v[112:115], v[96:111]
	v_cvt_pk_bf16_f32 v148, v80, v81
	v_cvt_pk_bf16_f32 v149, v82, v83
	v_cvt_pk_bf16_f32 v150, v84, v85
	v_cvt_pk_bf16_f32 v151, v86, v87
	v_cvt_pk_bf16_f32 v152, v88, v89
	v_cvt_pk_bf16_f32 v153, v90, v91
	v_cvt_pk_bf16_f32 v154, v92, v93
	v_cvt_pk_bf16_f32 v155, v94, v95
	v_add_u32_e32 v232, s41, v198
	ds_read_b128 v[156:159], v232 offset:34944
	ds_read_b128 v[172:175], v232 offset:34976
	ds_read_b128 v[176:179], v232 offset:35008
	ds_read_b128 v[186:189], v232 offset:35040
	v_lshlrev_b32_e32 v0, 1, v197
	v_add3_u32 v14, s41, v199, v0
	v_add_u32_e32 v15, 0x4000, v14
	v_add_u32_e32 v0, 0x5000, v14
	ds_read2_b64 v[2:5], v15 offset0:128 offset1:130
	ds_read2_b64 v[6:9], v15 offset0:132 offset1:134
	ds_read2_b64 v[10:13], v0 offset0:160 offset1:162
	ds_read2_b64 v[144:147], v0 offset0:164 offset1:166
	v_add_u32_e32 v236, 0x6000, v14
	v_add_u32_e32 v237, 0x7000, v14
	s_waitcnt lgkmcnt(3)
; #define MFMA32(a, b, c) __builtin_amdgcn_mfma_f32_32x32x16_bf16((a), (b), (c), 0, 0, 0)
; #define ATT_ISSUE_V(j_) do { const int k0_ = (j_) * 64; \
;         _Pragma("unroll") for (int i = 0; i < 2; ++i) { const int c = tid + i * NTHR, row = c >> 3, cc = c & 7; pv_[i] = *(const u32x4*)(Vt + (size_t)row * SEQ + k0_ + cc * 8); } } while (0)
;     ...
;                 float rs = 0.f;
; #pragma unroll
;                 for (int i = 0; i < 16; ++i) { const float pz = __builtin_amdgcn_exp2f(sacc[kb][i] + c0); sacc[kb][i] = pz; rs += pz; }
;                 l_run += rs;
;                 const bf16x8 pf0 = pack8(sacc[kb], 0), pf1 = pack8(sacc[kb], 1);
;                 __builtin_amdgcn_sched_barrier(0);
; #pragma unroll
;                 for (int d = 0; d < 2; ++d) { oacc[d] = MFMA32(vfa[d][0], pf0, oacc[d]); oacc[d] = MFMA32(vfa[d][1], pf1, oacc[d]); }
; #pragma unroll
;                 for (int d = 0; d < 2; ++d) { vfb[d][0] = ld_perm(Vs + (32 * (d + 2) + r) * VLD + 32 * kb + 4 * h2); vfb[d][1] = ld_perm(Vs + (32 * (d + 2) + r) * VLD + 32 * kb + 16 + 4 * h2); }
;                 if (kb == 1 && j + 1 < ntiles && amode != 5) ATT_ISSUE_V(j + 1);
;                 __builtin_amdgcn_sched_barrier(0);
; #pragma unroll
;                 for (int d = 0; d < 2; ++d) { oacc[d + 2] = MFMA32(vfb[d][0], pf0, oacc[d + 2]); oacc[d + 2] = MFMA32(vfb[d][1], pf1, oacc[d + 2]); }
;             }
;         } else if (j + 1 < ntiles && amode != 5) ATT_ISSUE_V(j + 1);
;     }
	v_mfma_f32_32x32x16_bf16 v[64:79], v[2:5], v[148:151], v[64:79]
	v_sub_f32_e32 v192, v96, v156
	v_exp_f32_e32 v96, v192
	v_sub_f32_e32 v193, v97, v157
	v_exp_f32_e32 v97, v193
	s_waitcnt lgkmcnt(1)
	v_mfma_f32_32x32x16_bf16 v[48:63], v[10:13], v[148:151], v[48:63]
	v_sub_f32_e32 v192, v98, v158
	v_exp_f32_e32 v98, v192
	v_sub_f32_e32 v193, v99, v159
	v_exp_f32_e32 v99, v193
	v_mfma_f32_32x32x16_bf16 v[64:79], v[6:9], v[152:155], v[64:79]
	ds_read2_b64 v[2:5], v237 offset0:228 offset1:230
	ds_read2_b64 v[6:9], v237 offset0:224 offset1:226
	v_sub_f32_e32 v192, v100, v172
	v_exp_f32_e32 v100, v192
	v_sub_f32_e32 v193, v101, v173
	v_exp_f32_e32 v101, v193
	s_waitcnt lgkmcnt(2)
	v_mfma_f32_32x32x16_bf16 v[48:63], v[144:147], v[152:155], v[48:63]
	ds_read2_b64 v[10:13], v236 offset0:192 offset1:194
	ds_read2_b64 v[144:147], v236 offset0:196 offset1:198
	v_sub_f32_e32 v192, v102, v174
	v_exp_f32_e32 v102, v192
	v_sub_f32_e32 v193, v103, v175
	v_exp_f32_e32 v103, v193
	s_waitcnt lgkmcnt(1)
	v_mfma_f32_32x32x16_bf16 v[32:47], v[10:13], v[148:151], v[32:47]
	v_sub_f32_e32 v192, v104, v176
	v_exp_f32_e32 v104, v192
	v_sub_f32_e32 v193, v105, v177
	v_exp_f32_e32 v105, v193
	v_mfma_f32_32x32x16_bf16 v[16:31], v[6:9], v[148:151], v[16:31]
	v_sub_f32_e32 v192, v106, v178
	v_exp_f32_e32 v106, v192
	v_sub_f32_e32 v193, v107, v179
	v_exp_f32_e32 v107, v193
	s_waitcnt lgkmcnt(0)
	v_mfma_f32_32x32x16_bf16 v[32:47], v[144:147], v[152:155], v[32:47]
	ds_read2_b64 v[6:9], v15 offset0:136 offset1:138
	ds_read2_b64 v[10:13], v15 offset0:140 offset1:142
	ds_read2_b64 v[144:147], v0 offset0:168 offset1:170
	ds_read2_b64 v[232:235], v0 offset0:172 offset1:174
	v_sub_f32_e32 v192, v108, v186
	v_exp_f32_e32 v108, v192
	v_sub_f32_e32 v193, v109, v187
	v_exp_f32_e32 v109, v193
	v_mfma_f32_32x32x16_bf16 v[16:31], v[2:5], v[152:155], v[16:31]
	v_sub_f32_e32 v192, v110, v188
	v_exp_f32_e32 v110, v192
	v_sub_f32_e32 v193, v111, v189
	v_exp_f32_e32 v111, v193
	v_cvt_pk_bf16_f32 v2, v96, v97
	v_cvt_pk_bf16_f32 v3, v98, v99
	v_cvt_pk_bf16_f32 v4, v100, v101
	v_cvt_pk_bf16_f32 v5, v102, v103
	v_cvt_pk_bf16_f32 v148, v104, v105
	v_cvt_pk_bf16_f32 v149, v106, v107
	v_cvt_pk_bf16_f32 v150, v108, v109
	v_cvt_pk_bf16_f32 v151, v110, v111
	s_waitcnt lgkmcnt(3)
	v_mfma_f32_32x32x16_bf16 v[64:79], v[6:9], v[2:5], v[64:79]
	v_add_f32_e32 v192, 0, v80
	v_add_f32_e32 v193, 0, v96
	v_add_f32_e32 v192, v81, v192
	v_add_f32_e32 v193, v97, v193
	s_waitcnt lgkmcnt(1)
	v_mfma_f32_32x32x16_bf16 v[48:63], v[144:147], v[2:5], v[48:63]
	v_add_f32_e32 v192, v82, v192
	v_add_f32_e32 v193, v98, v193
	v_add_f32_e32 v192, v83, v192
	v_add_f32_e32 v193, v99, v193
	v_mfma_f32_32x32x16_bf16 v[64:79], v[10:13], v[148:151], v[64:79]
	ds_read2_b64 v[6:9], v236 offset0:200 offset1:202
	ds_read2_b64 v[10:13], v236 offset0:204 offset1:206
	ds_read2_b64 v[144:147], v237 offset0:232 offset1:234
	ds_read2_b64 v[152:155], v237 offset0:236 offset1:238
	v_add_f32_e32 v192, v84, v192
	v_add_f32_e32 v193, v100, v193
	v_add_f32_e32 v192, v85, v192
	v_add_f32_e32 v193, v101, v193
	s_waitcnt lgkmcnt(4)
	v_mfma_f32_32x32x16_bf16 v[48:63], v[232:235], v[148:151], v[48:63]
	v_add_f32_e32 v192, v86, v192
	v_add_f32_e32 v193, v102, v193
	v_add_f32_e32 v192, v87, v192
	v_add_f32_e32 v193, v103, v193
	s_waitcnt lgkmcnt(3)
	v_mfma_f32_32x32x16_bf16 v[32:47], v[6:9], v[2:5], v[32:47]
	v_add_f32_e32 v192, v88, v192
	v_add_f32_e32 v193, v104, v193
	v_add_f32_e32 v192, v89, v192
	v_add_f32_e32 v193, v105, v193
	s_waitcnt lgkmcnt(1)
	v_mfma_f32_32x32x16_bf16 v[16:31], v[144:147], v[2:5], v[16:31]
	v_add_f32_e32 v192, v90, v192
	v_add_f32_e32 v193, v106, v193
	v_add_f32_e32 v192, v91, v192
	v_add_f32_e32 v193, v107, v193
	v_mfma_f32_32x32x16_bf16 v[32:47], v[10:13], v[148:151], v[32:47]
	v_add_f32_e32 v192, v92, v192
	v_add_f32_e32 v193, v108, v193
	v_add_f32_e32 v192, v93, v192
	v_add_f32_e32 v193, v109, v193
	s_waitcnt lgkmcnt(0)
	v_mfma_f32_32x32x16_bf16 v[16:31], v[152:155], v[148:151], v[16:31]
	v_add_f32_e32 v192, v94, v192
	v_add_f32_e32 v193, v110, v193
	v_add_f32_e32 v192, v95, v192
	v_add_f32_e32 v193, v111, v193
	v_add_f32_e32 v192, v183, v192
	v_add_f32_e32 v183, v192, v193
	s_add_i32 s60, s60, 1
	s_cmp_eq_u32 s59, s60
	s_cbranch_scc1 .LBB0_280
	s_mov_b32 s40, s4
	s_branch .LBB0_249

;     ...
;         if (active) {
; #pragma unroll
;             for (int kb = 0; kb < 2; ++kb) {
;                 constexpr int NB = KS / 4;
;                 const bf16_t* kp = Ks + (32 * kb + r) * KLD + 8 * h2;
;                 bf16x8 kf[2][4];
; #pragma unroll
;                 for (int e = 0; e < 4; ++e) kf[0][e] = *(const bf16x8*)(kp + 16 * e);
;                 f32x16 acc; for (int i = 0; i < 16; ++i) acc[i] = 0.f;
; #pragma unroll
;                 for (int bb = 0; bb < NB; ++bb) {
;                     if (bb + 1 < NB) {
; #pragma unroll
;                         for (int e = 0; e < 4; ++e) kf[(bb + 1) & 1][e] = *(const bf16x8*)(kp + 16 * (4 * (bb + 1) + e)); }
;                     __builtin_amdgcn_sched_barrier(0);
; #pragma unroll
;                     for (int e = 0; e < 4; ++e) acc = MFMA32(kf[bb & 1][e], qf[4 * bb + e], acc);
;                     __builtin_amdgcn_sched_barrier(0);
;                 }
;                 sacc[kb] = acc;
;             }
;         }
;         if (j + 1 < ntiles && amode != 5) ATT_ISSUE_K(j + 1);
;         if (active) {
;             const bool masked = (k0 + 63 > q0); const int qpos = q0 + r;
; #pragma unroll
;             for (int kb = 0; kb < 2; ++kb) {
;                 bf16x8 vfa[2][2], vfb[2][2];
; #pragma unroll
;                 for (int d = 0; d < 2; ++d) { vfa[d][0] = ld_perm(Vs + (32 * d + r) * VLD + 32 * kb + 4 * h2); vfa[d][1] = ld_perm(Vs + (32 * d + r) * VLD + 32 * kb + 16 + 4 * h2); }
;                 f32x4 c4[2];
;                 if (DECAY) {
; #pragma unroll
;                     for (int g = 0; g < 2; ++g) c4[g] = *(const f32x4*)(cks + 32 * kb + 8 * g + 4 * h2); }
;                 __builtin_amdgcn_sched_barrier(0);
;                 if (DECAY) {
; #pragma unroll
;                     for (int g = 0; g < 2; ++g)
; #pragma unroll
;                         for (int e = 0; e < 4; ++e) sacc[kb][4 * g + e] -= c4[g][e];
; #pragma unroll
;                     for (int g = 0; g < 2; ++g) c4[g] = *(const f32x4*)(cks + 32 * kb + 8 * (g + 2) + 4 * h2);
; #pragma unroll
;                     for (int g = 0; g < 2; ++g)
; #pragma unroll
;                         for (int e = 0; e < 4; ++e) sacc[kb][4 * (g + 2) + e] -= c4[g][e];
;                 }
;                 if (masked) {
; #pragma unroll
;                     for (int i = 0; i < 16; ++i) { if (k0 + 32 * kb + crow(i, h2) > qpos) sacc[kb][i] = -INFINITY; } }
.Lmla_fast:
	v_add3_u32 v0, s35, v198, v237
	ds_read_b128 v[2:5], v0
	ds_read_b128 v[6:9], v0 offset:32
	ds_read_b128 v[10:13], v0 offset:64
	ds_read_b128 v[96:99], v0 offset:96
	ds_read_b128 v[100:103], v0 offset:128
	ds_read_b128 v[104:107], v0 offset:160
	ds_read_b128 v[108:111], v0 offset:192
	ds_read_b128 v[160:163], v0 offset:224
	s_waitcnt lgkmcnt(7)
	v_mfma_f32_32x32x16_bf16 v[80:95], v[2:5], v[156:159], 0
	s_waitcnt lgkmcnt(6)
	v_mfma_f32_32x32x16_bf16 v[80:95], v[6:9], v[152:155], v[80:95]
	s_waitcnt lgkmcnt(5)
	v_mfma_f32_32x32x16_bf16 v[80:95], v[10:13], v[148:151], v[80:95]
	s_waitcnt lgkmcnt(4)
	v_mfma_f32_32x32x16_bf16 v[80:95], v[96:99], v[144:147], v[80:95]
	ds_read_b128 v[2:5], v0 offset:256
	ds_read_b128 v[6:9], v0 offset:288
	ds_read_b128 v[10:13], v0 offset:320
	ds_read_b128 v[96:99], v0 offset:352
	s_waitcnt lgkmcnt(7)
	v_mfma_f32_32x32x16_bf16 v[80:95], v[100:103], v[140:143], v[80:95]
	s_waitcnt lgkmcnt(6)
	v_mfma_f32_32x32x16_bf16 v[80:95], v[104:107], v[136:139], v[80:95]
	s_waitcnt lgkmcnt(5)
	v_mfma_f32_32x32x16_bf16 v[80:95], v[108:111], v[132:135], v[80:95]
	s_waitcnt lgkmcnt(4)
	v_mfma_f32_32x32x16_bf16 v[80:95], v[160:163], v[128:131], v[80:95]
	s_waitcnt lgkmcnt(3)
	v_mfma_f32_32x32x16_bf16 v[80:95], v[2:5], v[124:127], v[80:95]
	s_waitcnt lgkmcnt(2)
	v_mfma_f32_32x32x16_bf16 v[80:95], v[6:9], v[120:123], v[80:95]
	s_waitcnt lgkmcnt(1)
	v_mfma_f32_32x32x16_bf16 v[80:95], v[10:13], v[116:119], v[80:95]
	s_waitcnt lgkmcnt(0)
	v_mfma_f32_32x32x16_bf16 v[80:95], v[96:99], v[112:115], v[80:95]
	ds_read_b128 v[2:5], v0 offset:12800
	ds_read_b128 v[6:9], v0 offset:12832
	ds_read_b128 v[10:13], v0 offset:12864
	ds_read_b128 v[160:163], v0 offset:12896
	ds_read_b128 v[164:167], v0 offset:12928
	ds_read_b128 v[168:171], v0 offset:12960
	ds_read_b128 v[172:175], v0 offset:12992
	ds_read_b128 v[176:179], v0 offset:13024
	s_waitcnt lgkmcnt(7)
	v_mfma_f32_32x32x16_bf16 v[96:111], v[2:5], v[156:159], 0
	s_waitcnt lgkmcnt(6)
	v_mfma_f32_32x32x16_bf16 v[96:111], v[6:9], v[152:155], v[96:111]
	s_waitcnt lgkmcnt(5)
	v_mfma_f32_32x32x16_bf16 v[96:111], v[10:13], v[148:151], v[96:111]
	v_add_f32_e32 v14, v197, v80
	v_exp_f32_e32 v80, v14
	v_add_f32_e32 v15, v197, v81
	v_exp_f32_e32 v81, v15
	s_waitcnt lgkmcnt(4)
	v_mfma_f32_32x32x16_bf16 v[96:111], v[160:163], v[144:147], v[96:111]
	ds_read_b128 v[2:5], v0 offset:13056
	ds_read_b128 v[6:9], v0 offset:13088
	ds_read_b128 v[10:13], v0 offset:13120
	ds_read_b128 v[160:163], v0 offset:13152
	v_add_f32_e32 v14, v197, v82
	v_exp_f32_e32 v82, v14
	v_add_f32_e32 v15, v197, v83
	v_exp_f32_e32 v83, v15
	s_waitcnt lgkmcnt(7)
	v_mfma_f32_32x32x16_bf16 v[96:111], v[164:167], v[140:143], v[96:111]
	v_add_f32_e32 v14, v197, v84
	v_exp_f32_e32 v84, v14
	v_add_f32_e32 v15, v197, v85
	v_exp_f32_e32 v85, v15
	s_waitcnt lgkmcnt(6)
	v_mfma_f32_32x32x16_bf16 v[96:111], v[168:171], v[136:139], v[96:111]
	v_add_f32_e32 v14, v197, v86
	v_exp_f32_e32 v86, v14
	v_add_f32_e32 v15, v197, v87
	v_exp_f32_e32 v87, v15
	s_waitcnt lgkmcnt(5)
	v_mfma_f32_32x32x16_bf16 v[96:111], v[172:175], v[132:135], v[96:111]
	v_add_f32_e32 v14, v197, v88
	v_exp_f32_e32 v88, v14
	v_add_f32_e32 v15, v197, v89
	v_exp_f32_e32 v89, v15
	s_waitcnt lgkmcnt(4)
	v_mfma_f32_32x32x16_bf16 v[96:111], v[176:179], v[128:131], v[96:111]
	v_add_f32_e32 v14, v197, v90
	v_exp_f32_e32 v90, v14
	v_add_f32_e32 v15, v197, v91
	v_exp_f32_e32 v91, v15
	s_waitcnt lgkmcnt(3)
	v_mfma_f32_32x32x16_bf16 v[96:111], v[2:5], v[124:127], v[96:111]
	v_add_f32_e32 v14, v197, v92
	v_exp_f32_e32 v92, v14
	v_add_f32_e32 v15, v197, v93
	v_exp_f32_e32 v93, v15
	s_waitcnt lgkmcnt(2)
	v_mfma_f32_32x32x16_bf16 v[96:111], v[6:9], v[120:123], v[96:111]
	v_add_f32_e32 v14, v197, v94
	v_exp_f32_e32 v94, v14
	v_add_f32_e32 v15, v197, v95
	v_exp_f32_e32 v95, v15
	s_waitcnt lgkmcnt(1)
	v_mfma_f32_32x32x16_bf16 v[96:111], v[10:13], v[116:119], v[96:111]
	v_cvt_pk_bf16_f32 v186, v80, v81
	v_cvt_pk_bf16_f32 v187, v82, v83
	v_cvt_pk_bf16_f32 v188, v84, v85
	v_cvt_pk_bf16_f32 v189, v86, v87
	s_waitcnt lgkmcnt(0)
	v_mfma_f32_32x32x16_bf16 v[96:111], v[160:163], v[112:115], v[96:111]
	v_cvt_pk_bf16_f32 v214, v88, v89
	v_cvt_pk_bf16_f32 v215, v90, v91
	v_cvt_pk_bf16_f32 v216, v92, v93
	v_cvt_pk_bf16_f32 v217, v94, v95
	v_lshlrev_b32_e32 v0, 1, v233
	v_add3_u32 v15, s35, v234, v0
	v_add_u32_e32 v176, 0x6000, v15
	v_add_u32_e32 v180, 0x7000, v15
	ds_read2_b64 v[2:5], v176 offset0:128 offset1:130
	ds_read2_b64 v[6:9], v176 offset0:132 offset1:134
	ds_read2_b64 v[10:13], v180 offset0:160 offset1:162
	ds_read2_b64 v[172:175], v180 offset0:164 offset1:166
	v_add_u32_e32 v0, s34, v248
	v_mad_i64_i32 v[192:193], s[0:1], v0, s7, v[208:209]
	global_load_dwordx4 v[164:167], v[192:193], off
	v_add_u32_e32 v0, s34, v247
	v_mad_i64_i32 v[192:193], s[0:1], v0, s7, v[210:211]
	global_load_dwordx4 v[160:163], v[192:193], off
	v_add_u32_e32 v0, s34, v246
	v_mad_i64_i32 v[192:193], s[0:1], v0, s7, v[212:213]
	global_load_dwordx4 v[168:171], v[192:193], off
	s_add_i32 s4, s34, 64
	s_waitcnt lgkmcnt(3)
; #define MFMA32(a, b, c) __builtin_amdgcn_mfma_f32_32x32x16_bf16((a), (b), (c), 0, 0, 0)
; #define ATT_ISSUE_V(j_) do { const int k0_ = (j_) * 64; \
;         _Pragma("unroll") for (int i = 0; i < 2; ++i) { const int c = tid + i * NTHR, row = c >> 3, cc = c & 7; pv_[i] = *(const u32x4*)(Vt + (size_t)row * SEQ + k0_ + cc * 8); } } while (0)
;     ...
;                 const bf16x8 pf0 = pack8(sacc[kb], 0), pf1 = pack8(sacc[kb], 1);
;                 __builtin_amdgcn_sched_barrier(0);
; #pragma unroll
;                 for (int d = 0; d < 2; ++d) { oacc[d] = MFMA32(vfa[d][0], pf0, oacc[d]); oacc[d] = MFMA32(vfa[d][1], pf1, oacc[d]); }
; #pragma unroll
;                 for (int d = 0; d < 2; ++d) { vfb[d][0] = ld_perm(Vs + (32 * (d + 2) + r) * VLD + 32 * kb + 4 * h2); vfb[d][1] = ld_perm(Vs + (32 * (d + 2) + r) * VLD + 32 * kb + 16 + 4 * h2); }
;                 if (kb == 1 && j + 1 < ntiles && amode != 5) ATT_ISSUE_V(j + 1);
;                 __builtin_amdgcn_sched_barrier(0);
; #pragma unroll
;                 for (int d = 0; d < 2; ++d) { oacc[d + 2] = MFMA32(vfb[d][0], pf0, oacc[d + 2]); oacc[d + 2] = MFMA32(vfb[d][1], pf1, oacc[d + 2]); }
;             }
	v_mfma_f32_32x32x16_bf16 v[64:79], v[2:5], v[186:189], v[64:79]
	v_add_u32_e32 v0, 0x9000, v15
	v_add_u32_e32 v15, 0x8000, v15
	v_add_f32_e32 v14, v197, v96
	v_exp_f32_e32 v96, v14
	v_add_f32_e32 v192, v197, v97
	v_exp_f32_e32 v97, v192
	s_waitcnt lgkmcnt(1)
	v_mfma_f32_32x32x16_bf16 v[48:63], v[10:13], v[186:189], v[48:63]
	v_add_f32_e32 v14, v197, v98
	v_exp_f32_e32 v98, v14
	v_add_f32_e32 v192, v197, v99
	v_exp_f32_e32 v99, v192
	v_mfma_f32_32x32x16_bf16 v[64:79], v[6:9], v[214:217], v[64:79]
	ds_read2_b64 v[2:5], v0 offset0:228 offset1:230
	ds_read2_b64 v[6:9], v0 offset0:224 offset1:226
	v_add_f32_e32 v14, v197, v100
	v_exp_f32_e32 v100, v14
	v_add_f32_e32 v192, v197, v101
	v_exp_f32_e32 v101, v192
	s_waitcnt lgkmcnt(2)
	v_mfma_f32_32x32x16_bf16 v[48:63], v[172:175], v[214:217], v[48:63]
	ds_read2_b64 v[10:13], v15 offset0:192 offset1:194
	ds_read2_b64 v[172:175], v15 offset0:196 offset1:198
	v_add_f32_e32 v14, v197, v102
	v_exp_f32_e32 v102, v14
	v_add_f32_e32 v192, v197, v103
	v_exp_f32_e32 v103, v192
	s_waitcnt lgkmcnt(1)
	v_mfma_f32_32x32x16_bf16 v[32:47], v[10:13], v[186:189], v[32:47]
	v_add_f32_e32 v14, v197, v104
	v_exp_f32_e32 v104, v14
	v_add_f32_e32 v192, v197, v105
	v_exp_f32_e32 v105, v192
	v_mfma_f32_32x32x16_bf16 v[16:31], v[6:9], v[186:189], v[16:31]
	v_add_f32_e32 v14, v197, v106
	v_exp_f32_e32 v106, v14
	v_add_f32_e32 v192, v197, v107
	v_exp_f32_e32 v107, v192
	s_waitcnt lgkmcnt(0)
	v_mfma_f32_32x32x16_bf16 v[32:47], v[172:175], v[214:217], v[32:47]
	ds_read2_b64 v[10:13], v176 offset0:136 offset1:138
	ds_read2_b64 v[172:175], v176 offset0:140 offset1:142
	ds_read2_b64 v[176:179], v180 offset0:168 offset1:170
	ds_read2_b64 v[180:183], v180 offset0:172 offset1:174
	v_add_f32_e32 v14, v197, v108
	v_exp_f32_e32 v108, v14
	v_add_f32_e32 v192, v197, v109
	v_exp_f32_e32 v109, v192
	v_mfma_f32_32x32x16_bf16 v[16:31], v[2:5], v[214:217], v[16:31]
	v_add_f32_e32 v14, v197, v110
	v_exp_f32_e32 v110, v14
	v_add_f32_e32 v192, v197, v111
	v_exp_f32_e32 v111, v192
	v_cvt_pk_bf16_f32 v2, v96, v97
	v_cvt_pk_bf16_f32 v3, v98, v99
	v_cvt_pk_bf16_f32 v4, v100, v101
	v_cvt_pk_bf16_f32 v5, v102, v103
	v_cvt_pk_bf16_f32 v6, v104, v105
	v_cvt_pk_bf16_f32 v7, v106, v107
	v_cvt_pk_bf16_f32 v8, v108, v109
	v_cvt_pk_bf16_f32 v9, v110, v111
	v_lshl_add_u64 v[186:187], s[4:5], 1, v[202:203]
	v_lshl_add_u64 v[188:189], v[186:187], 0, v[204:205]
	v_lshl_add_u64 v[186:187], v[186:187], 0, v[206:207]
	s_waitcnt lgkmcnt(3)
	v_mfma_f32_32x32x16_bf16 v[64:79], v[10:13], v[2:5], v[64:79]
	v_add_f32_e32 v14, 0, v80
	v_add_f32_e32 v192, 0, v96
	v_add_f32_e32 v14, v81, v14
	v_add_f32_e32 v192, v97, v192
	s_waitcnt lgkmcnt(1)
	v_mfma_f32_32x32x16_bf16 v[48:63], v[176:179], v[2:5], v[48:63]
	v_add_f32_e32 v14, v82, v14
	v_add_f32_e32 v192, v98, v192
	v_add_f32_e32 v14, v83, v14
	v_add_f32_e32 v192, v99, v192
	v_mfma_f32_32x32x16_bf16 v[64:79], v[172:175], v[6:9], v[64:79]
	v_add_f32_e32 v14, v84, v14
	v_add_f32_e32 v192, v100, v192
	v_add_f32_e32 v14, v85, v14
	v_add_f32_e32 v192, v101, v192
	s_waitcnt lgkmcnt(0)
	v_mfma_f32_32x32x16_bf16 v[48:63], v[180:183], v[6:9], v[48:63]
	global_load_dwordx4 v[172:175], v[186:187], off
	global_load_dwordx4 v[176:179], v[188:189], off
	ds_read2_b64 v[10:13], v15 offset0:200 offset1:202
	ds_read2_b64 v[180:183], v15 offset0:204 offset1:206
	ds_read2_b64 v[186:189], v0 offset0:232 offset1:234
	ds_read2_b64 v[214:217], v0 offset0:236 offset1:238
	v_add_f32_e32 v14, v86, v14
	v_add_f32_e32 v192, v102, v192
	v_add_f32_e32 v14, v87, v14
	v_add_f32_e32 v192, v103, v192
	s_waitcnt lgkmcnt(3)
	v_mfma_f32_32x32x16_bf16 v[32:47], v[10:13], v[2:5], v[32:47]
	v_add_f32_e32 v14, v88, v14
	v_add_f32_e32 v192, v104, v192
	v_add_f32_e32 v14, v89, v14
	v_add_f32_e32 v192, v105, v192
	s_waitcnt lgkmcnt(1)
	v_mfma_f32_32x32x16_bf16 v[16:31], v[186:189], v[2:5], v[16:31]
	v_add_f32_e32 v14, v90, v14
	v_add_f32_e32 v192, v106, v192
	v_add_f32_e32 v14, v91, v14
	v_add_f32_e32 v192, v107, v192
	v_mfma_f32_32x32x16_bf16 v[32:47], v[180:183], v[6:9], v[32:47]
	v_add_f32_e32 v14, v92, v14
	v_add_f32_e32 v192, v108, v192
	v_add_f32_e32 v14, v93, v14
	v_add_f32_e32 v192, v109, v192
	s_waitcnt lgkmcnt(0)
	v_mfma_f32_32x32x16_bf16 v[16:31], v[214:217], v[6:9], v[16:31]
	v_add_f32_e32 v14, v94, v14
	v_add_f32_e32 v192, v110, v192
	v_add_f32_e32 v14, v95, v14
	v_add_f32_e32 v192, v111, v192
	v_add_f32_e32 v193, v199, v14
	v_add_f32_e32 v199, v193, v192
	s_add_i32 s41, s41, 1
	s_cmp_eq_u32 s40, s41
	s_cbranch_scc1 .LBB0_318
	s_mov_b32 s34, s4
	s_branch .LBB0_291
